# fused residual+norm epilogues: L2 touch loads for the later residual row batches issued with the first batch
# baseline (speedup 1.0000x reference)
.LBB0_345:
	s_lshl_b32 s35, s0, 8
	s_add_i32 s1, s35, 0xfffff000
	v_lshl_add_u32 v178, s68, 8, v196
	v_add_u32_e32 v170, s35, v194
	s_lshr_b32 s1, s1, 11
	v_ashrrev_i32_e32 v179, 31, v178
	v_ashrrev_i32_e32 v171, 31, v170
	s_mulk_i32 s1, 0x1800
	s_cmp_gt_i32 s0, 15
	v_lshl_add_u64 v[172:173], v[178:179], 1, s[20:21]
	v_lshlrev_b64 v[168:169], 11, v[170:171]
	s_cselect_b32 s18, s1, 0x6000
	v_lshl_add_u64 v[112:113], v[172:173], 0, v[168:169]
	s_lshl_b64 s[70:71], s[18:19], 2
	global_load_dwordx4 v[174:177], v[112:113], off
	global_load_dwordx4 v[182:185], v[112:113], off offset:256
	s_mov_b64 s[98:99], 0x10000
	v_lshl_add_u64 v[244:245], v[112:113], 0, s[98:99]
	global_load_dword v247, v[244:245], off
	global_load_dword v247, v[244:245], off offset:256
	s_mov_b64 s[98:99], 0x18000
	v_lshl_add_u64 v[244:245], v[112:113], 0, s[98:99]
	global_load_dword v247, v[244:245], off
	global_load_dword v247, v[244:245], off offset:256
	s_mov_b64 s[98:99], 0x40000
	v_lshl_add_u64 v[244:245], v[112:113], 0, s[98:99]
	global_load_dword v247, v[244:245], off
	global_load_dword v247, v[244:245], off offset:256
	s_mov_b64 s[98:99], 0x48000
	v_lshl_add_u64 v[244:245], v[112:113], 0, s[98:99]
	global_load_dword v247, v[244:245], off
	global_load_dword v247, v[244:245], off offset:256
	s_mov_b64 s[98:99], 0x50000
	v_lshl_add_u64 v[244:245], v[112:113], 0, s[98:99]
	global_load_dword v247, v[244:245], off
	global_load_dword v247, v[244:245], off offset:256
	s_mov_b64 s[98:99], 0x58000
	v_lshl_add_u64 v[244:245], v[112:113], 0, s[98:99]
	global_load_dword v247, v[244:245], off
	global_load_dword v247, v[244:245], off offset:256
	s_add_u32 s72, s33, s70
	s_addc_u32 s73, s76, s71
	v_lshl_add_u64 v[112:113], v[178:179], 2, s[72:73]
	global_load_dwordx4 v[132:135], v[112:113], off
	global_load_dwordx4 v[128:131], v[112:113], off offset:16
	global_load_dwordx4 v[120:123], v[112:113], off offset:512
	s_nop 0
	global_load_dwordx4 v[112:115], v[112:113], off offset:528
	v_or_b32_e32 v144, 16, v170
	v_ashrrev_i32_e32 v145, 31, v144
	v_lshlrev_b64 v[180:181], 11, v[144:145]
	v_lshl_add_u64 v[144:145], v[172:173], 0, v[180:181]
	global_load_dwordx4 v[148:151], v[144:145], off
	s_nop 0
	global_load_dwordx4 v[144:147], v[144:145], off offset:256
	v_and_b32_e32 v187, 64, v217
	v_xor_b32_e32 v186, 16, v217
	v_add_u32_e32 v223, 64, v187
	v_cmp_lt_i32_e32 vcc, v186, v223
	s_waitcnt vmcnt(0)
	v_and_b32_e32 v187, 0xffff0000, v174
	v_cndmask_b32_e32 v186, v217, v186, vcc
	v_lshlrev_b32_e32 v222, 2, v186
	v_lshlrev_b32_e32 v186, 16, v174
	v_lshlrev_b32_e32 v174, 16, v175
	v_and_b32_e32 v175, 0xffff0000, v175
	v_lshlrev_b32_e32 v188, 16, v176
	v_and_b32_e32 v189, 0xffff0000, v176
	v_lshlrev_b32_e32 v176, 16, v177
	v_and_b32_e32 v177, 0xffff0000, v177
	v_lshlrev_b32_e32 v190, 16, v182
	v_and_b32_e32 v191, 0xffff0000, v182
	v_lshlrev_b32_e32 v182, 16, v183
	v_and_b32_e32 v183, 0xffff0000, v183
	v_pk_fma_f32 v[142:143], v[142:143], v[134:135], v[174:175]
	v_pk_fma_f32 v[140:141], v[140:141], v[132:133], v[186:187]
	v_pk_fma_f32 v[138:139], v[138:139], v[130:131], v[176:177]
	v_pk_fma_f32 v[136:137], v[136:137], v[128:129], v[188:189]
	v_lshlrev_b32_e32 v192, 16, v184
	v_and_b32_e32 v193, 0xffff0000, v184
	v_lshlrev_b32_e32 v184, 16, v185
	v_and_b32_e32 v185, 0xffff0000, v185
	v_pk_fma_f32 v[126:127], v[126:127], v[122:123], v[182:183]
	v_pk_fma_f32 v[124:125], v[124:125], v[120:121], v[190:191]
	v_mul_f32_e32 v174, v141, v141
	v_mul_f32_e32 v175, v143, v143
	v_mul_f32_e32 v176, v137, v137
	v_mul_f32_e32 v177, v139, v139
	v_pk_fma_f32 v[118:119], v[118:119], v[114:115], v[184:185]
	v_pk_fma_f32 v[116:117], v[116:117], v[112:113], v[192:193]
	v_mul_f32_e32 v182, v125, v125
	v_mul_f32_e32 v183, v127, v127
	v_fmac_f32_e32 v174, v140, v140
	v_fmac_f32_e32 v175, v142, v142
	v_fmac_f32_e32 v176, v136, v136
	v_fmac_f32_e32 v177, v138, v138
	v_mul_f32_e32 v184, v117, v117
	v_mul_f32_e32 v185, v119, v119
	v_fmac_f32_e32 v182, v124, v124
	v_fmac_f32_e32 v183, v126, v126
	v_add_f32_e32 v174, v174, v175
	v_add_f32_e32 v175, v176, v177
	v_fmac_f32_e32 v184, v116, v116
	v_fmac_f32_e32 v185, v118, v118
	v_add_f32_e32 v176, v182, v183
	v_add_f32_e32 v174, v174, v175
	v_add_f32_e32 v174, v174, v176
	v_add_f32_e32 v175, v184, v185
	v_add_f32_e32 v174, v175, v174
	ds_bpermute_b32 v175, v222, v174
	v_xor_b32_e32 v176, 32, v217
	v_cmp_lt_i32_e32 vcc, v176, v223
	s_waitcnt lgkmcnt(0)
	v_add_f32_e32 v174, v174, v175
	v_cndmask_b32_e32 v176, v217, v176, vcc
	v_lshlrev_b32_e32 v223, 2, v176
	ds_bpermute_b32 v175, v223, v174
	s_and_saveexec_b64 s[72:73], s[4:5]
	s_cbranch_execz .LBB0_347
	s_waitcnt lgkmcnt(0)
	v_add_f32_e32 v174, v174, v175
	ds_write_b32 v221, v174

.LBB0_508:
	s_lshl_b32 s71, s0, 8
	s_add_i32 s1, s71, 0xfffff000
	v_lshl_add_u32 v170, s78, 8, v196
	v_add_u32_e32 v186, s71, v194
	s_lshr_b32 s1, s1, 11
	v_ashrrev_i32_e32 v171, 31, v170
	v_ashrrev_i32_e32 v187, 31, v186
	s_mulk_i32 s1, 0x1800
	s_cmp_gt_i32 s0, 15
	v_lshl_add_u64 v[190:191], v[170:171], 1, s[38:39]
	v_lshlrev_b64 v[168:169], 11, v[186:187]
	s_cselect_b32 s28, s1, 0x6000
	v_lshl_add_u64 v[112:113], v[190:191], 0, v[168:169]
	s_lshl_b64 s[80:81], s[28:29], 2
	global_load_dwordx4 v[172:175], v[112:113], off
	global_load_dwordx4 v[176:179], v[112:113], off offset:256
	s_mov_b64 s[98:99], 0x10000
	v_lshl_add_u64 v[244:245], v[112:113], 0, s[98:99]
	global_load_dword v247, v[244:245], off
	global_load_dword v247, v[244:245], off offset:256
	s_mov_b64 s[98:99], 0x18000
	v_lshl_add_u64 v[244:245], v[112:113], 0, s[98:99]
	global_load_dword v247, v[244:245], off
	global_load_dword v247, v[244:245], off offset:256
	s_mov_b64 s[98:99], 0x40000
	v_lshl_add_u64 v[244:245], v[112:113], 0, s[98:99]
	global_load_dword v247, v[244:245], off
	global_load_dword v247, v[244:245], off offset:256
	s_mov_b64 s[98:99], 0x48000
	v_lshl_add_u64 v[244:245], v[112:113], 0, s[98:99]
	global_load_dword v247, v[244:245], off
	global_load_dword v247, v[244:245], off offset:256
	s_mov_b64 s[98:99], 0x50000
	v_lshl_add_u64 v[244:245], v[112:113], 0, s[98:99]
	global_load_dword v247, v[244:245], off
	global_load_dword v247, v[244:245], off offset:256
	s_mov_b64 s[98:99], 0x58000
	v_lshl_add_u64 v[244:245], v[112:113], 0, s[98:99]
	global_load_dword v247, v[244:245], off
	global_load_dword v247, v[244:245], off offset:256
	s_add_u32 s62, s96, s80
	s_addc_u32 s63, s97, s81
	v_lshl_add_u64 v[112:113], v[170:171], 2, s[62:63]
	global_load_dwordx4 v[132:135], v[112:113], off
	global_load_dwordx4 v[128:131], v[112:113], off offset:16
	global_load_dwordx4 v[120:123], v[112:113], off offset:512
	s_nop 0
	global_load_dwordx4 v[112:115], v[112:113], off offset:528
	v_or_b32_e32 v144, 16, v186
	v_ashrrev_i32_e32 v145, 31, v144
	v_lshlrev_b64 v[180:181], 11, v[144:145]
	v_lshl_add_u64 v[144:145], v[190:191], 0, v[180:181]
	global_load_dwordx4 v[148:151], v[144:145], off
	s_nop 0
	global_load_dwordx4 v[144:147], v[144:145], off offset:256
	v_and_b32_e32 v183, 64, v217
	v_xor_b32_e32 v182, 16, v217
	v_add_u32_e32 v223, 64, v183
	v_cmp_lt_i32_e32 vcc, v182, v223
	s_waitcnt vmcnt(0)
	v_and_b32_e32 v183, 0xffff0000, v172
	v_cndmask_b32_e32 v182, v217, v182, vcc
	v_lshlrev_b32_e32 v222, 2, v182
	v_lshlrev_b32_e32 v182, 16, v172
	v_lshlrev_b32_e32 v172, 16, v173
	v_and_b32_e32 v173, 0xffff0000, v173
	v_lshlrev_b32_e32 v184, 16, v174
	v_and_b32_e32 v185, 0xffff0000, v174
	v_lshlrev_b32_e32 v174, 16, v175
	v_and_b32_e32 v175, 0xffff0000, v175
	v_lshlrev_b32_e32 v188, 16, v176
	v_and_b32_e32 v189, 0xffff0000, v176
	v_lshlrev_b32_e32 v176, 16, v177
	v_and_b32_e32 v177, 0xffff0000, v177
	v_pk_fma_f32 v[142:143], v[142:143], v[134:135], v[172:173]
	v_pk_fma_f32 v[140:141], v[140:141], v[132:133], v[182:183]
	v_pk_fma_f32 v[138:139], v[138:139], v[130:131], v[174:175]
	v_pk_fma_f32 v[136:137], v[136:137], v[128:129], v[184:185]
	v_lshlrev_b32_e32 v192, 16, v178
	v_and_b32_e32 v193, 0xffff0000, v178
	v_lshlrev_b32_e32 v178, 16, v179
	v_and_b32_e32 v179, 0xffff0000, v179
	v_pk_fma_f32 v[126:127], v[126:127], v[122:123], v[176:177]
	v_pk_fma_f32 v[124:125], v[124:125], v[120:121], v[188:189]
	v_mul_f32_e32 v172, v141, v141
	v_mul_f32_e32 v173, v143, v143
	v_mul_f32_e32 v174, v137, v137
	v_mul_f32_e32 v175, v139, v139
	v_pk_fma_f32 v[118:119], v[118:119], v[114:115], v[178:179]
	v_pk_fma_f32 v[116:117], v[116:117], v[112:113], v[192:193]
	v_mul_f32_e32 v176, v125, v125
	v_mul_f32_e32 v177, v127, v127
	v_fmac_f32_e32 v172, v140, v140
	v_fmac_f32_e32 v173, v142, v142
	v_fmac_f32_e32 v174, v136, v136
	v_fmac_f32_e32 v175, v138, v138
	v_mul_f32_e32 v178, v117, v117
	v_mul_f32_e32 v179, v119, v119
	v_fmac_f32_e32 v176, v124, v124
	v_fmac_f32_e32 v177, v126, v126
	v_add_f32_e32 v172, v172, v173
	v_add_f32_e32 v173, v174, v175
	v_fmac_f32_e32 v178, v116, v116
	v_fmac_f32_e32 v179, v118, v118
	v_add_f32_e32 v174, v176, v177
	v_add_f32_e32 v172, v172, v173
	v_add_f32_e32 v172, v172, v174
	v_add_f32_e32 v173, v178, v179
	v_add_f32_e32 v172, v173, v172
	ds_bpermute_b32 v173, v222, v172
	v_xor_b32_e32 v174, 32, v217
	v_cmp_lt_i32_e32 vcc, v174, v223
	s_waitcnt lgkmcnt(0)
	v_add_f32_e32 v172, v172, v173
	v_cndmask_b32_e32 v174, v217, v174, vcc
	v_lshlrev_b32_e32 v223, 2, v174
	ds_bpermute_b32 v173, v223, v172
	s_and_saveexec_b64 s[82:83], s[4:5]
	s_cbranch_execz .LBB0_510
	s_waitcnt lgkmcnt(0)
	v_add_f32_e32 v172, v172, v173
	ds_write_b32 v221, v172

.LBB0_1789:
	s_lshl_b32 s61, s0, 8
	s_add_i32 s1, s61, 0xfffff000
	v_lshl_add_u32 v170, s68, 8, v190
	v_add_u32_e32 v178, s61, v188
	s_lshr_b32 s1, s1, 11
	v_ashrrev_i32_e32 v171, 31, v170
	v_ashrrev_i32_e32 v179, 31, v178
	s_mulk_i32 s1, 0x1800
	s_cmp_gt_i32 s0, 15
	v_lshl_add_u64 v[180:181], v[170:171], 1, s[20:21]
	v_lshlrev_b64 v[168:169], 11, v[178:179]
	s_cselect_b32 s16, s1, 0x6000
	v_lshl_add_u64 v[112:113], v[180:181], 0, v[168:169]
	s_lshl_b64 s[70:71], s[16:17], 2
	global_load_dwordx4 v[174:177], v[112:113], off
	global_load_dwordx4 v[182:185], v[112:113], off offset:256
	s_mov_b64 s[98:99], 0x10000
	v_lshl_add_u64 v[244:245], v[112:113], 0, s[98:99]
	global_load_dword v247, v[244:245], off
	global_load_dword v247, v[244:245], off offset:256
	s_mov_b64 s[98:99], 0x18000
	v_lshl_add_u64 v[244:245], v[112:113], 0, s[98:99]
	global_load_dword v247, v[244:245], off
	global_load_dword v247, v[244:245], off offset:256
	s_mov_b64 s[98:99], 0x40000
	v_lshl_add_u64 v[244:245], v[112:113], 0, s[98:99]
	global_load_dword v247, v[244:245], off
	global_load_dword v247, v[244:245], off offset:256
	s_mov_b64 s[98:99], 0x48000
	v_lshl_add_u64 v[244:245], v[112:113], 0, s[98:99]
	global_load_dword v247, v[244:245], off
	global_load_dword v247, v[244:245], off offset:256
	s_mov_b64 s[98:99], 0x50000
	v_lshl_add_u64 v[244:245], v[112:113], 0, s[98:99]
	global_load_dword v247, v[244:245], off
	global_load_dword v247, v[244:245], off offset:256
	s_mov_b64 s[98:99], 0x58000
	v_lshl_add_u64 v[244:245], v[112:113], 0, s[98:99]
	global_load_dword v247, v[244:245], off
	global_load_dword v247, v[244:245], off offset:256
	s_add_u32 s58, s43, s70
	s_addc_u32 s59, s76, s71
	v_lshl_add_u64 v[112:113], v[170:171], 2, s[58:59]
	global_load_dwordx4 v[132:135], v[112:113], off
	global_load_dwordx4 v[128:131], v[112:113], off offset:16
	global_load_dwordx4 v[120:123], v[112:113], off offset:512
	s_nop 0
	global_load_dwordx4 v[112:115], v[112:113], off offset:528
	v_or_b32_e32 v144, 16, v178
	v_ashrrev_i32_e32 v145, 31, v144
	v_lshlrev_b64 v[172:173], 11, v[144:145]
	v_lshl_add_u64 v[144:145], v[180:181], 0, v[172:173]
	global_load_dwordx4 v[148:151], v[144:145], off
	s_nop 0
	global_load_dwordx4 v[144:147], v[144:145], off offset:256
	v_and_b32_e32 v187, 64, v211
	v_xor_b32_e32 v186, 16, v211
	v_add_u32_e32 v217, 64, v187
	v_cmp_lt_i32_e32 vcc, v186, v217
	s_waitcnt vmcnt(0)
	v_and_b32_e32 v187, 0xffff0000, v174
	v_cndmask_b32_e32 v186, v211, v186, vcc
	v_lshlrev_b32_e32 v216, 2, v186
	v_lshlrev_b32_e32 v186, 16, v174
	v_lshlrev_b32_e32 v174, 16, v175
	v_and_b32_e32 v175, 0xffff0000, v175
	v_lshlrev_b32_e32 v218, 16, v176
	v_and_b32_e32 v219, 0xffff0000, v176
	v_lshlrev_b32_e32 v176, 16, v177
	v_and_b32_e32 v177, 0xffff0000, v177
	v_lshlrev_b32_e32 v220, 16, v182
	v_and_b32_e32 v221, 0xffff0000, v182
	v_lshlrev_b32_e32 v182, 16, v183
	v_and_b32_e32 v183, 0xffff0000, v183
	v_pk_fma_f32 v[142:143], v[142:143], v[134:135], v[174:175]
	v_pk_fma_f32 v[140:141], v[140:141], v[132:133], v[186:187]
	v_pk_fma_f32 v[138:139], v[138:139], v[130:131], v[176:177]
	v_pk_fma_f32 v[136:137], v[136:137], v[128:129], v[218:219]
	v_lshlrev_b32_e32 v222, 16, v184
	v_and_b32_e32 v223, 0xffff0000, v184
	v_lshlrev_b32_e32 v184, 16, v185
	v_and_b32_e32 v185, 0xffff0000, v185
	v_pk_fma_f32 v[126:127], v[126:127], v[122:123], v[182:183]
	v_pk_fma_f32 v[124:125], v[124:125], v[120:121], v[220:221]
	v_mul_f32_e32 v174, v141, v141
	v_mul_f32_e32 v175, v143, v143
	v_mul_f32_e32 v176, v137, v137
	v_mul_f32_e32 v177, v139, v139
	v_pk_fma_f32 v[118:119], v[118:119], v[114:115], v[184:185]
	v_pk_fma_f32 v[116:117], v[116:117], v[112:113], v[222:223]
	v_mul_f32_e32 v182, v125, v125
	v_mul_f32_e32 v183, v127, v127
	v_fmac_f32_e32 v174, v140, v140
	v_fmac_f32_e32 v175, v142, v142
	v_fmac_f32_e32 v176, v136, v136
	v_fmac_f32_e32 v177, v138, v138
	v_mul_f32_e32 v184, v117, v117
	v_mul_f32_e32 v185, v119, v119
	v_fmac_f32_e32 v182, v124, v124
	v_fmac_f32_e32 v183, v126, v126
	v_add_f32_e32 v174, v174, v175
	v_add_f32_e32 v175, v176, v177
	v_fmac_f32_e32 v184, v116, v116
	v_fmac_f32_e32 v185, v118, v118
	v_add_f32_e32 v176, v182, v183
	v_add_f32_e32 v174, v174, v175
	v_add_f32_e32 v174, v174, v176
	v_add_f32_e32 v175, v184, v185
	v_add_f32_e32 v174, v175, v174
	ds_bpermute_b32 v175, v216, v174
	v_xor_b32_e32 v176, 32, v211
	v_cmp_lt_i32_e32 vcc, v176, v217
	s_waitcnt lgkmcnt(0)
	v_add_f32_e32 v174, v174, v175
	v_cndmask_b32_e32 v176, v211, v176, vcc
	v_lshlrev_b32_e32 v217, 2, v176
	ds_bpermute_b32 v175, v217, v174
	s_and_saveexec_b64 s[72:73], s[4:5]
	s_cbranch_execz .LBB0_1791
	s_waitcnt lgkmcnt(0)
	v_add_f32_e32 v174, v174, v175
	ds_write_b32 v215, v174

.LBB0_1952:
	s_lshl_b32 s41, s10, 8
	s_add_i32 s11, s41, 0xfffff000
	v_lshl_add_u32 v168, s50, 8, v176
	v_add_u32_e32 v170, s41, v174
	s_lshr_b32 s11, s11, 11
	v_ashrrev_i32_e32 v169, 31, v168
	v_ashrrev_i32_e32 v171, 31, v170
	s_mulk_i32 s11, 0x1800
	s_cmp_gt_i32 s10, 15
	v_lshl_add_u64 v[172:173], v[168:169], 1, s[20:21]
	v_lshlrev_b64 v[112:113], 11, v[170:171]
	s_cselect_b32 s16, s11, 0x6000
	v_lshl_add_u64 v[112:113], v[172:173], 0, v[112:113]
	s_lshl_b64 s[54:55], s[16:17], 2
	global_load_dwordx4 v[204:207], v[112:113], off
	global_load_dwordx4 v[208:211], v[112:113], off offset:256
	s_mov_b64 s[98:99], 0x10000
	v_lshl_add_u64 v[244:245], v[112:113], 0, s[98:99]
	global_load_dword v247, v[244:245], off
	global_load_dword v247, v[244:245], off offset:256
	s_mov_b64 s[98:99], 0x18000
	v_lshl_add_u64 v[244:245], v[112:113], 0, s[98:99]
	global_load_dword v247, v[244:245], off
	global_load_dword v247, v[244:245], off offset:256
	s_mov_b64 s[98:99], 0x40000
	v_lshl_add_u64 v[244:245], v[112:113], 0, s[98:99]
	global_load_dword v247, v[244:245], off
	global_load_dword v247, v[244:245], off offset:256
	s_mov_b64 s[98:99], 0x48000
	v_lshl_add_u64 v[244:245], v[112:113], 0, s[98:99]
	global_load_dword v247, v[244:245], off
	global_load_dword v247, v[244:245], off offset:256
	s_mov_b64 s[98:99], 0x50000
	v_lshl_add_u64 v[244:245], v[112:113], 0, s[98:99]
	global_load_dword v247, v[244:245], off
	global_load_dword v247, v[244:245], off offset:256
	s_mov_b64 s[98:99], 0x58000
	v_lshl_add_u64 v[244:245], v[112:113], 0, s[98:99]
	global_load_dword v247, v[244:245], off
	global_load_dword v247, v[244:245], off offset:256
	s_add_u32 s54, s64, s54
	s_addc_u32 s55, s65, s55
	v_lshl_add_u64 v[112:113], v[168:169], 2, s[54:55]
	global_load_dwordx4 v[132:135], v[112:113], off
	global_load_dwordx4 v[124:127], v[112:113], off offset:16
	global_load_dwordx4 v[116:119], v[112:113], off offset:512
	s_nop 0
	global_load_dwordx4 v[112:115], v[112:113], off offset:528
	v_or_b32_e32 v144, 16, v170
	v_ashrrev_i32_e32 v145, 31, v144
	v_lshlrev_b64 v[144:145], 11, v[144:145]
	v_lshl_add_u64 v[144:145], v[172:173], 0, v[144:145]
	global_load_dwordx4 v[148:151], v[144:145], off
	s_nop 0
	global_load_dwordx4 v[144:147], v[144:145], off offset:256
	v_and_b32_e32 v203, 64, v197
	v_xor_b32_e32 v202, 16, v197
	v_add_u32_e32 v203, 64, v203
	v_cmp_lt_i32_e32 vcc, v202, v203
	s_waitcnt vmcnt(0)
	v_lshlrev_b32_e32 v212, 16, v204
	v_and_b32_e32 v213, 0xffff0000, v204
	v_lshlrev_b32_e32 v204, 16, v205
	v_and_b32_e32 v205, 0xffff0000, v205
	v_lshlrev_b32_e32 v214, 16, v206
	v_and_b32_e32 v215, 0xffff0000, v206
	v_lshlrev_b32_e32 v206, 16, v207
	v_and_b32_e32 v207, 0xffff0000, v207
	v_lshlrev_b32_e32 v216, 16, v208
	v_and_b32_e32 v217, 0xffff0000, v208
	v_lshlrev_b32_e32 v208, 16, v209
	v_and_b32_e32 v209, 0xffff0000, v209
	v_pk_fma_f32 v[142:143], v[142:143], v[134:135], v[204:205]
	v_pk_fma_f32 v[140:141], v[140:141], v[132:133], v[212:213]
	v_pk_fma_f32 v[138:139], v[138:139], v[126:127], v[206:207]
	v_pk_fma_f32 v[136:137], v[136:137], v[124:125], v[214:215]
	v_lshlrev_b32_e32 v218, 16, v210
	v_and_b32_e32 v219, 0xffff0000, v210
	v_lshlrev_b32_e32 v210, 16, v211
	v_and_b32_e32 v211, 0xffff0000, v211
	v_pk_fma_f32 v[130:131], v[130:131], v[118:119], v[208:209]
	v_pk_fma_f32 v[128:129], v[128:129], v[116:117], v[216:217]
	v_mul_f32_e32 v204, v141, v141
	v_mul_f32_e32 v205, v143, v143
	v_mul_f32_e32 v206, v137, v137
	v_mul_f32_e32 v207, v139, v139
	v_pk_fma_f32 v[122:123], v[122:123], v[114:115], v[210:211]
	v_pk_fma_f32 v[120:121], v[120:121], v[112:113], v[218:219]
	v_mul_f32_e32 v208, v129, v129
	v_mul_f32_e32 v209, v131, v131
	v_fmac_f32_e32 v204, v140, v140
	v_fmac_f32_e32 v205, v142, v142
	v_fmac_f32_e32 v206, v136, v136
	v_fmac_f32_e32 v207, v138, v138
	v_mul_f32_e32 v210, v121, v121
	v_mul_f32_e32 v211, v123, v123
	v_fmac_f32_e32 v208, v128, v128
	v_fmac_f32_e32 v209, v130, v130
	v_add_f32_e32 v204, v204, v205
	v_add_f32_e32 v205, v206, v207
	v_fmac_f32_e32 v210, v120, v120
	v_fmac_f32_e32 v211, v122, v122
	v_add_f32_e32 v206, v208, v209
	v_add_f32_e32 v204, v204, v205
	v_cndmask_b32_e32 v202, v197, v202, vcc
	v_add_f32_e32 v204, v204, v206
	v_add_f32_e32 v205, v210, v211
	v_lshlrev_b32_e32 v202, 2, v202
	v_add_f32_e32 v204, v205, v204
	ds_bpermute_b32 v205, v202, v204
	v_xor_b32_e32 v206, 32, v197
	v_cmp_lt_i32_e32 vcc, v206, v203
	s_waitcnt lgkmcnt(0)
	v_add_f32_e32 v204, v204, v205
	v_cndmask_b32_e32 v203, v197, v206, vcc
	v_lshlrev_b32_e32 v203, 2, v203
	ds_bpermute_b32 v205, v203, v204
	s_and_saveexec_b64 s[54:55], s[0:1]
	s_cbranch_execz .LBB0_1954
	s_waitcnt lgkmcnt(0)
	v_add_f32_e32 v204, v204, v205
	ds_write_b32 v201, v204
